# v126 plus L2 warm-up of each wave's 16 activation rows before the beta/alpha GEMV row loop
# baseline (speedup 1.0000x reference)
; __device__ __forceinline__ int ptid_(int wave) { int l_; asm volatile("v_mbcnt_lo_u32_b32 %0, -1, 0\n\tv_mbcnt_hi_u32_b32 %0, -1, %0" : "=v"(l_)); return (wave << 6) | l_; }
; __device__ void ba_item(const Params& p, int L, int rp) {
;     ...
;   const float* wba = misc + MF_WBA + (L >> 1) * 8192;
;   const float* rowss = misc + MF_RSP + (L == 0 ? 0L : 2L * MTOK * 16);
;   int tid = ptid_(p.tid); asm volatile("" : "+v"(tid));
;   const int wid = tid >> 6, lane = tid & 63;
;   f32x4 wr_[8][4];
;   _Pragma("unroll") for (int j = 0; j < 8; ++j) _Pragma("unroll") for (int e4 = 0; e4 < 4; ++e4)
;     wr_[j][e4] = *(const f32x4*)(wba + j * 1024 + lane * 16 + e4 * 4);
;   for (int bt = 0; bt < 8; ++bt) {
;     bf16x8 h0[2], h1[2]; f32x4 ps[2][4];
;     _Pragma("unroll") for (int u = 0; u < 2; ++u) {
;       const int row = rp * 128 + wid * 16 + bt * 2 + u;
;       const bfu* hr = hb + (long)row * 1024 + lane * 16;
;       h0[u] = *(const bf16x8*)hr; h1[u] = *(const bf16x8*)(hr + 8);
;       _Pragma("unroll") for (int i = 0; i < 4; ++i) ps[u][i] = *(const f32x4*)(rowss + (long)row * 16 + i * 4);
.LBB0_612:
	s_cmpk_gt_i32 s18, 0x6ff
	s_mov_b64 s[0:1], -1
	s_cbranch_scc0 .LBB0_628
	v_mbcnt_lo_u32_b32 v0, -1, 0
	v_mbcnt_hi_u32_b32 v0, -1, v0
	s_mov_b64 s[0:1], 0x1000
	s_waitcnt vmcnt(0)
	v_or_b32_e32 v130, s33, v0
	v_mov_b32_e32 v131, v1
	v_and_b32_e32 v132, 63, v130
	v_lshlrev_b32_e32 v0, 6, v132
	v_lshl_add_u64 v[114:115], s[26:27], 0, v[0:1]
	s_waitcnt lgkmcnt(0)
	v_lshl_add_u64 v[34:35], v[114:115], 0, s[0:1]
	s_mov_b64 s[0:1], 0x2000
	v_add_co_u32_e32 v30, vcc, s56, v114
	v_lshl_add_u64 v[46:47], v[114:115], 0, s[0:1]
	s_mov_b64 s[0:1], 0x3000
	v_addc_co_u32_e32 v31, vcc, 0, v115, vcc
	v_lshl_add_u64 v[66:67], v[114:115], 0, s[0:1]
	s_mov_b64 s[0:1], 0x4000
	v_add_co_u32_e32 v62, vcc, s63, v114
	s_waitcnt vmcnt(0)
	v_lshl_add_u64 v[78:79], v[114:115], 0, s[0:1]
	s_mov_b64 s[0:1], 0x5000
	v_addc_co_u32_e32 v63, vcc, 0, v115, vcc
	v_lshl_add_u64 v[98:99], v[114:115], 0, s[0:1]
	s_movk_i32 s0, 0x6000
	v_add_co_u32_e32 v94, vcc, s0, v114
	s_mov_b64 s[0:1], 0x6000
	v_lshl_add_u64 v[110:111], v[114:115], 0, s[0:1]
	s_mov_b64 s[0:1], 0x7000
	v_addc_co_u32_e32 v95, vcc, 0, v115, vcc
	v_lshl_add_u64 v[126:127], v[114:115], 0, s[0:1]
	s_movk_i32 s0, 0x7000
	global_load_dwordx4 v[2:5], v0, s[26:27]
	global_load_dwordx4 v[6:9], v0, s[26:27] offset:16
	global_load_dwordx4 v[10:13], v0, s[26:27] offset:32
	global_load_dwordx4 v[14:17], v0, s[26:27] offset:48
	global_load_dwordx4 v[18:21], v[34:35], off offset:16
	global_load_dwordx4 v[22:25], v[34:35], off offset:32
	global_load_dwordx4 v[26:29], v[30:31], off offset:-4096
	s_nop 0
	global_load_dwordx4 v[30:33], v[30:31], off
	s_nop 0
	global_load_dwordx4 v[34:37], v[34:35], off offset:48
	s_nop 0
	global_load_dwordx4 v[38:41], v[46:47], off offset:16
	global_load_dwordx4 v[42:45], v[46:47], off offset:32
	s_nop 0
	global_load_dwordx4 v[46:49], v[46:47], off offset:48
	s_nop 0
	global_load_dwordx4 v[50:53], v[66:67], off offset:16
	global_load_dwordx4 v[54:57], v[66:67], off offset:32
	global_load_dwordx4 v[58:61], v[62:63], off offset:-4096
	s_nop 0
	global_load_dwordx4 v[62:65], v[62:63], off
	s_nop 0
	global_load_dwordx4 v[66:69], v[66:67], off offset:48
	s_nop 0
	global_load_dwordx4 v[70:73], v[78:79], off offset:16
	global_load_dwordx4 v[74:77], v[78:79], off offset:32
	s_nop 0
	global_load_dwordx4 v[78:81], v[78:79], off offset:48
	s_nop 0
	global_load_dwordx4 v[82:85], v[98:99], off offset:16
	global_load_dwordx4 v[86:89], v[98:99], off offset:32
	global_load_dwordx4 v[90:93], v[94:95], off offset:-4096
	s_nop 0
	global_load_dwordx4 v[94:97], v[94:95], off
	s_nop 0
	global_load_dwordx4 v[98:101], v[98:99], off offset:48
	s_nop 0
	global_load_dwordx4 v[102:105], v[110:111], off offset:16
	global_load_dwordx4 v[106:109], v[110:111], off offset:32
	s_nop 0
	global_load_dwordx4 v[110:113], v[110:111], off offset:48
	v_add_co_u32_e32 v122, vcc, s0, v114
	v_ashrrev_i32_e32 v0, 2, v130
	s_nop 0
	v_addc_co_u32_e32 v123, vcc, 0, v115, vcc
	global_load_dwordx4 v[114:117], v[126:127], off offset:16
	global_load_dwordx4 v[118:121], v[126:127], off offset:32
	s_nop 0
	global_load_dwordx4 v[122:125], v[122:123], off
	s_nop 0
	global_load_dwordx4 v[126:129], v[126:127], off offset:48
	v_and_b32_e32 v133, -16, v0
	v_lshlrev_b32_e32 v0, 5, v132
	v_readlane_b32 s0, v252, 18
	v_lshl_add_u64 v[154:155], s[80:81], 0, v[0:1]
	v_add_u32_e32 v0, s19, v132
	v_lshlrev_b32_e32 v130, 2, v132
	v_readlane_b32 s1, v252, 19
	v_readlane_b32 s80, v253, 52
	v_xor_b32_e32 v166, 0x80, v130
	v_lshl_add_u64 v[156:157], s[0:1], 0, v[130:131]
	v_xor_b32_e32 v167, 64, v130
	v_xor_b32_e32 v168, 32, v130
	v_xor_b32_e32 v169, 16, v130
	v_xor_b32_e32 v170, 8, v130
	v_xor_b32_e32 v171, 4, v130
	v_lshlrev_b64 v[130:131], 2, v[0:1]
	v_readlane_b32 s92, v254, 0
	v_readlane_b32 s93, v254, 1
	v_readlane_b32 s94, v254, 2
	v_readlane_b32 s95, v254, 3
	v_readlane_b32 s24, v254, 62
	s_mov_b32 s22, -16
	v_cmp_gt_u32_e32 vcc, 8, v132
	v_cmp_lt_u32_e64 s[38:39], 3, v132
	v_cmp_eq_u32_e64 s[40:41], 0, v132
	v_cmp_eq_u32_e64 s[42:43], 1, v132
	v_cmp_eq_u32_e64 s[44:45], 2, v132
	v_cmp_eq_u32_e64 s[46:47], 3, v132
	v_cmp_eq_u32_e64 s[48:49], 4, v132
	v_cmp_eq_u32_e64 s[50:51], 5, v132
	v_cmp_eq_u32_e64 s[52:53], 6, v132
	v_cmp_eq_u32_e64 s[54:55], 7, v132
	v_lshl_add_u64 v[158:159], s[94:95], 0, v[130:131]
	v_lshl_add_u64 v[160:161], s[92:93], 0, v[130:131]
	v_add_u32_e32 v0, s20, v133
	v_readlane_b32 s25, v254, 63
	v_readlane_b32 s81, v253, 53
	v_readlane_b32 s82, v253, 54
	v_readlane_b32 s83, v253, 55
	v_readlane_b32 s84, v253, 56
	v_readlane_b32 s85, v253, 57
	v_readlane_b32 s86, v253, 58
	v_readlane_b32 s87, v253, 59
	v_readlane_b32 s88, v253, 60
	v_readlane_b32 s89, v253, 61
	v_readlane_b32 s90, v253, 62
	v_readlane_b32 s91, v253, 63
	v_add_u32_e32 v204, 0xfffc8000, v0
	v_ashrrev_i32_e32 v205, 31, v204
	v_lshlrev_b64 v[206:207], 11, v[204:205]
	v_lshl_add_u64 v[206:207], v[154:155], 0, v[206:207]
	v_mov_b32_e32 v210, 0x800
	v_mov_b32_e32 v211, 0
	global_load_dword v212, v[206:207], off
	v_lshl_add_u64 v[206:207], v[206:207], 0, v[210:211]
	global_load_dword v212, v[206:207], off
	v_lshl_add_u64 v[206:207], v[206:207], 0, v[210:211]
	global_load_dword v212, v[206:207], off
	v_lshl_add_u64 v[206:207], v[206:207], 0, v[210:211]
	global_load_dword v212, v[206:207], off
	v_lshl_add_u64 v[206:207], v[206:207], 0, v[210:211]
	global_load_dword v212, v[206:207], off
	v_lshl_add_u64 v[206:207], v[206:207], 0, v[210:211]
	global_load_dword v212, v[206:207], off
	v_lshl_add_u64 v[206:207], v[206:207], 0, v[210:211]
	global_load_dword v212, v[206:207], off
	v_lshl_add_u64 v[206:207], v[206:207], 0, v[210:211]
	global_load_dword v212, v[206:207], off
	v_lshl_add_u64 v[206:207], v[206:207], 0, v[210:211]
	global_load_dword v212, v[206:207], off
	v_lshl_add_u64 v[206:207], v[206:207], 0, v[210:211]
	global_load_dword v212, v[206:207], off
	v_lshl_add_u64 v[206:207], v[206:207], 0, v[210:211]
	global_load_dword v212, v[206:207], off
	v_lshl_add_u64 v[206:207], v[206:207], 0, v[210:211]
	global_load_dword v212, v[206:207], off
	v_lshl_add_u64 v[206:207], v[206:207], 0, v[210:211]
	global_load_dword v212, v[206:207], off
	v_lshl_add_u64 v[206:207], v[206:207], 0, v[210:211]
	global_load_dword v212, v[206:207], off
	v_lshl_add_u64 v[206:207], v[206:207], 0, v[210:211]
	global_load_dword v212, v[206:207], off
	v_lshl_add_u64 v[206:207], v[206:207], 0, v[210:211]
	global_load_dword v212, v[206:207], off
	v_lshlrev_b64 v[208:209], 6, v[204:205]
	v_lshl_add_u64 v[208:209], s[24:25], 0, v[208:209]
	global_load_dword v212, v[208:209], off
	global_load_dword v212, v[208:209], off offset:128
	global_load_dword v212, v[208:209], off offset:256
	global_load_dword v212, v[208:209], off offset:384
	global_load_dword v212, v[208:209], off offset:512
	global_load_dword v212, v[208:209], off offset:640
	global_load_dword v212, v[208:209], off offset:768
	global_load_dword v212, v[208:209], off offset:896
	s_branch .LBB0_616
